# v11 + P2: helper waves run the last 4 neighbourhood-attention items of their SIMD partner after their weight conversions
# speedup vs baseline: 1.0048x; 1.0048x over previous
; #define ALDS __attribute__((address_space(3)))
; #define ATT_Q_DMA() do { unsigned qo_ = kD - klb; asm volatile("" : "+v"(qo_) :: "memory");     \
;         _Pragma("unroll") for (int c = 0; c < 8; ++c) \
;         __builtin_amdgcn_global_load_lds((const unsigned*)(qb + 1024 * c + (qo_ ^ (unsigned)((c & 3) << 6))), (ALDS unsigned*)(klb + 1024u * c), 16, 0, 0); } while (0)
; __device__ __forceinline__ void na_phase(const bf16* qkv, bf16* out, const float* rpb, ldsp lds, int vcu, int G, int tid_in) {
;     ...
;     if (wave >= 4) return;
;     constexpr size_t PITCH = 128, PLANE = pg8::PLANE; constexpr int NUNITS = 2048;
;     const int per = (NUNITS + G - 1) / G; const int u_lo = vcu * per, u_hi = (u_lo + per < NUNITS) ? u_lo + per : NUNITS;
;     for (int U2 = 2 * u_lo; U2 < 2 * u_hi; ++U2) { const int U = U2 >> 1;
;         int bh_, rq_; if (G == 256) { const int x_ = vcu >> 5, c_ = vcu & 31, i_ = U - u_lo; bh_ = x_ * 4 + (i_ >> 1); rq_ = (i_ & 1) * 32 + c_; } else { bh_ = U >> 6; rq_ = U & 63; }
;         const int b = bh_ >> 4, h = bh_ & 15, row = 4 * rq_ + wave, j = U2 & 1;
;         const int tokb = b * 16384, qc = 32 * j + r32;
;         const char* qb = (const char*)(qkv + (size_t)h * PLANE + (size_t)(tokb + row * 64 + 32 * j) * PITCH);
;         ATT_Q_DMA();
;         const int rs = min(max(row - 4, 0), 248), cs = min(max(qc - 8, 0), 48);
;         const char* kb = (const char*)(qkv + (size_t)(16 + h) * PLANE); const char* vb = (const char*)(qkv + (size_t)(32 + h) * PLANE);
;         const unsigned lane_off = (unsigned)((lane >> 4) * (int)(PITCH * 2) + (lane & 15) * 16);
;         const ALDS float* tbh = tb + h * 465;
.LBB0_152:
	s_or_b64 exec, exec, s[6:7]
	s_ashr_i32 s60, s41, 6
	s_cmp_lt_i32 s60, 4
	s_waitcnt lgkmcnt(0)
	s_mov_b32 s99, 0
	s_barrier
	s_cbranch_scc0 .LBB0_169
.Lhja_entry:
	s_abs_i32 s6, s24
	v_cvt_f32_u32_e32 v1, s6
	s_sub_i32 s9, 0, s6
	s_add_i32 s7, s24, 0x7ff
	s_xor_b32 s8, s7, s24
	v_rcp_iflag_f32_e32 v1, v1
	s_abs_i32 s7, s7
	s_ashr_i32 s8, s8, 31
	v_mul_f32_e32 v1, 0x4f7ffffe, v1
	v_cvt_u32_f32_e32 v1, v1
	s_nop 0
	v_readfirstlane_b32 s10, v1
	s_mul_i32 s9, s9, s10
	s_mul_hi_u32 s9, s10, s9
	s_add_i32 s10, s10, s9
	s_mul_hi_u32 s9, s7, s10
	s_mul_i32 s10, s9, s6
	s_sub_i32 s7, s7, s10
	s_add_i32 s11, s9, 1
	s_sub_i32 s10, s7, s6
	s_cmp_ge_u32 s7, s6
	s_cselect_b32 s9, s11, s9
	s_cselect_b32 s7, s10, s7
	s_add_i32 s10, s9, 1
	s_cmp_ge_u32 s7, s6
	s_cselect_b32 s6, s10, s9
	s_xor_b32 s6, s6, s8
	s_sub_i32 s6, s6, s8
	s_mul_i32 s61, s6, s83
	s_add_i32 s6, s61, s6
	s_min_i32 s6, s6, 0x800
	s_lshl_b32 s62, s61, 1
	s_lshl_b32 s63, s6, 1
	s_sub_i32 s6, s63, 4
	s_cmp_eq_u32 s99, 1
	s_cselect_b32 s62, s6, s62
	s_cselect_b32 s63, s63, s6
	s_cmp_ge_i32 s62, s63
	s_cbranch_scc1 .LBB0_169
	v_bfe_u32 v1, v0, 5, 1
	s_lshl_b32 s64, s81, 8
	v_lshrrev_b32_e32 v12, 3, v0
	v_and_b32_e32 v15, 12, v0
	s_add_i32 s64, s64, 0
	v_bfe_u32 v212, v0, 4, 2
	v_bitop3_b32 v5, v1, v0, 15 bitop3:0x78
	v_lshlrev_b32_e32 v9, 3, v1
	v_bfe_u32 v10, v0, 2, 2
	v_lshlrev_b32_e32 v11, 2, v1
	v_and_b32_e32 v12, 2, v12
	v_bfe_u32 v13, v0, 1, 1
	v_or_b32_e32 v1, v1, v15
	v_and_b32_e32 v2, 63, v0
	v_and_b32_e32 v211, 31, v0
	s_add_i32 s6, s64, 0x2000
	v_and_b32_e32 v3, 15, v0
	v_bitop3_b32 v7, v212, v0, 15 bitop3:0x78
	v_lshlrev_b32_e32 v0, 3, v0
	v_or_b32_e32 v16, v11, v10
	v_bitop3_b32 v1, v12, v1, v13 bitop3:0x36
	v_and_or_b32 v0, v0, 8, s6
	v_lshlrev_b32_e32 v16, 8, v16
	v_lshlrev_b32_e32 v1, 4, v1
	v_add3_u32 v214, v0, v16, v1
	v_or_b32_e32 v1, 8, v11
	v_lshlrev_b32_e32 v4, 8, v211
	v_or_b32_e32 v14, v12, v13
	v_or_b32_e32 v10, v1, v10
	v_lshrrev_b32_e32 v1, 2, v1
	v_lshl_or_b32 v5, v5, 4, v4
	v_bitop3_b32 v1, v1, v14, v15 bitop3:0x36
	v_lshlrev_b32_e32 v3, 4, v3
	v_lshlrev_b32_e32 v10, 8, v10
	v_lshlrev_b32_e32 v1, 4, v1
	v_add_u32_e32 v216, s64, v5
	v_and_b32_e32 v5, 64, v252
	v_lshlrev_b32_e32 v6, 8, v212
	v_lshlrev_b32_e32 v8, 6, v212
	v_add3_u32 v215, v10, v0, v1
	v_or3_b32 v0, v3, v9, v4
	v_add_u32_e32 v5, 64, v5
	v_bitop3_b32 v8, v8, v6, v3 bitop3:0xde
	v_add_u32_e32 v218, s64, v0
	s_cmpk_lg_i32 s24, 0x100
	v_lshlrev_b32_e32 v0, 3, v7
	v_cmp_lt_i32_e32 vcc, v210, v5
	v_lshl_or_b32 v213, v7, 4, v6
	v_add_u32_e32 v217, s6, v8
	s_cselect_b64 s[14:15], -1, 0
	s_ashr_i32 s6, s83, 3
	v_or_b32_e32 v192, v6, v3
	v_mov_b32_e32 v1, 0
	v_lshlrev_b32_e32 v3, 4, v2
	v_xor_b32_e32 v2, 32, v0
	v_xor_b32_e32 v4, 64, v0
	v_xor_b32_e32 v6, 0x60, v0
	v_cndmask_b32_e32 v5, v252, v210, vcc
	s_and_b32 s65, s83, 31
	s_and_b32 s66, s6, -4
	v_mov_b32_e32 v193, v1
	v_xor_b32_e32 v219, 16, v218
	v_xor_b32_e32 v220, 32, v218
	v_xor_b32_e32 v221, 48, v218
	v_xor_b32_e32 v222, 64, v218
	v_xor_b32_e32 v223, 0x50, v218
	v_xor_b32_e32 v224, 0x60, v218
	v_xor_b32_e32 v225, 0x70, v218
	v_xor_b32_e32 v226, 0x80, v218
	v_xor_b32_e32 v227, 0x90, v218
	v_xor_b32_e32 v228, 0xa0, v218
	v_xor_b32_e32 v229, 0xb0, v218
	v_xor_b32_e32 v230, 0xc0, v218
	v_xor_b32_e32 v231, 0xd0, v218
	v_xor_b32_e32 v232, 0xe0, v218
	v_xor_b32_e32 v233, 0xf0, v218
	v_lshlrev_b32_e32 v234, 2, v5
	v_or_b32_e32 v235, 3, v11
	v_sub_u32_e32 v236, v11, v211
	s_mov_b64 s[38:39], 0
	s_mov_b64 s[40:41], 0x400
	s_add_i32 s67, s64, 0x400
	s_mov_b64 s[42:43], 0x800
	s_add_i32 s68, s64, 0x800
	s_mov_b64 s[44:45], 0xc00
	s_add_i32 s69, s64, 0xc00
	s_mov_b64 s[46:47], 0x1000
	s_add_i32 s70, s64, 0x1000
	s_mov_b64 s[48:49], 0x1400
	s_add_i32 s71, s64, 0x1400
	s_mov_b64 s[50:51], 0x1800
	s_add_i32 s74, s64, 0x1800
	s_mov_b64 s[52:53], 0x1c00
	s_add_i32 s75, s64, 0x1c00
	s_mov_b64 s[54:55], 0x8000000
	s_mov_b64 s[56:57], 0x10000000
	v_add_u32_e32 v237, s64, v3
	v_lshlrev_b32_e32 v194, 1, v0
	v_lshlrev_b32_e32 v196, 1, v2
	v_lshlrev_b32_e32 v198, 1, v4
	v_lshlrev_b32_e32 v200, 1, v6
	v_mov_b32_e32 v238, 0xf149f2ca
	s_branch .LBB0_156

; #define TID() fresh_tid(wave)
; __device__ __forceinline__ void tr_load(const float* W, int N, int nblk, int item, int lane, f32x4 (&wv)[8]) {
;     const int kb = item / nblk, nb = item % nblk, k0 = 64 * kb, n0 = 32 * nb;
; #pragma unroll
;     for (int i = 0; i < 8; ++i) wv[i] = *(const f32x4*)(W + (size_t)(k0 + 8 * i + (lane >> 3)) * N + n0 + 4 * (lane & 7));
; }
; __global__ void __launch_bounds__(NWAVES * 64, 2) mk_fwd(Args args) {
;     ...
;     if (wave >= 4) {
;         const int lane = TID() & 63, gw4 = vcu * 4 + (wave - 4), NGW4 = G * 4;
;         convert_matrix(args.in[4], DM, DM, (bf16*)(ws + WS_WO0), nullptr, 0, 1.f, scr, gw4, NGW4, lane);
;         convert_matrix(args.in[6], DM, DFF, (bf16*)(ws + WS_W10), args.in[5], 0, 1.f, scr, gw4, NGW4, lane);
.LBB0_169:
	s_cmp_eq_u32 s99, 1
	s_cbranch_scc1 .LBB0_221
	s_cmpk_gt_u32 s72, 0xff
	s_cbranch_scc0 .LBB0_221
	s_lshl_b32 s6, s83, 2
	v_mov_b32_e32 v0, v252
	s_add_i32 s6, s73, s6
	s_add_i32 s41, s6, -4
	v_and_b32_e32 v38, 63, v0
	s_lshl_b32 s40, s24, 2
	s_cmpk_gt_i32 s41, 0x7ff
	v_lshrrev_b32_e32 v32, 3, v38
	v_lshlrev_b32_e32 v45, 4, v38
	v_lshlrev_b32_e32 v33, 3, v38
	s_cbranch_scc1 .LBB0_175
	s_ashr_i32 s8, s41, 31
	s_lshr_b32 s8, s8, 26
	s_add_i32 s8, s41, s8
	s_load_dwordx2 s[6:7], s[0:1], 0x20
	s_and_b32 s9, s8, 0xffffffc0
	s_sub_i32 s8, s41, s9
	s_lshl_b32 s8, s8, 5
	v_lshrrev_b32_e32 v39, 3, v38
	v_or_b32_e32 v24, s9, v39
	s_ashr_i32 s9, s8, 31
	s_lshl_b64 s[8:9], s[8:9], 2
	s_waitcnt lgkmcnt(0)
	s_add_u32 s8, s6, s8
	s_addc_u32 s9, s7, s9
	v_and_b32_e32 v36, 0x70, v45
	v_mov_b32_e32 v37, 0
	v_ashrrev_i32_e32 v25, 31, v24
	v_lshl_add_u64 v[26:27], s[8:9], 0, v[36:37]
	v_lshlrev_b64 v[0:1], 13, v[24:25]
	v_lshl_add_u64 v[8:9], v[26:27], 0, v[0:1]
	v_or_b32_e32 v0, 8, v24
	v_ashrrev_i32_e32 v1, 31, v0
	v_lshlrev_b64 v[0:1], 13, v[0:1]
	v_lshl_add_u64 v[10:11], v[26:27], 0, v[0:1]
	global_load_dwordx4 v[0:3], v[8:9], off
	global_load_dwordx4 v[4:7], v[10:11], off
	v_or_b32_e32 v8, 16, v24
	v_ashrrev_i32_e32 v9, 31, v8
	v_lshlrev_b64 v[8:9], 13, v[8:9]
	v_lshl_add_u64 v[16:17], v[26:27], 0, v[8:9]
	v_or_b32_e32 v8, 24, v24
	v_ashrrev_i32_e32 v9, 31, v8
	v_lshlrev_b64 v[8:9], 13, v[8:9]
	v_lshl_add_u64 v[18:19], v[26:27], 0, v[8:9]
	global_load_dwordx4 v[8:11], v[16:17], off
	global_load_dwordx4 v[12:15], v[18:19], off
	v_or_b32_e32 v16, 32, v24
	v_ashrrev_i32_e32 v17, 31, v16
	v_lshlrev_b64 v[16:17], 13, v[16:17]
	v_lshl_add_u64 v[28:29], v[26:27], 0, v[16:17]
	v_or_b32_e32 v16, 40, v24
	v_ashrrev_i32_e32 v17, 31, v16
	v_lshlrev_b64 v[16:17], 13, v[16:17]
	v_lshl_add_u64 v[30:31], v[26:27], 0, v[16:17]
	global_load_dwordx4 v[16:19], v[28:29], off
	global_load_dwordx4 v[20:23], v[30:31], off
	v_or_b32_e32 v28, 48, v24
	v_ashrrev_i32_e32 v29, 31, v28
	v_or_b32_e32 v24, 56, v24
	v_lshlrev_b64 v[28:29], 13, v[28:29]
	v_ashrrev_i32_e32 v25, 31, v24
	v_lshl_add_u64 v[34:35], v[26:27], 0, v[28:29]
	v_lshlrev_b64 v[24:25], 13, v[24:25]
	v_lshl_add_u64 v[40:41], v[26:27], 0, v[24:25]
	global_load_dwordx4 v[24:27], v[34:35], off
	global_load_dwordx4 v[28:31], v[40:41], off
	v_add_u32_e32 v41, s78, v36
	v_lshl_add_u64 v[34:35], s[6:7], 0, v[36:37]
	v_and_b32_e32 v36, 56, v33
	v_mul_u32_u24_e32 v40, 0x84, v36
	v_lshlrev_b32_e32 v36, 1, v36
	v_mul_u32_u24_e32 v42, 0x84, v39
	v_lshl_add_u64 v[36:37], s[18:19], 0, v[36:37]
	s_mov_b64 s[6:7], 0x1c00000
	v_lshlrev_b32_e32 v43, 2, v39
	s_lshl_b32 s9, s40, 5
	v_lshl_add_u64 v[36:37], v[36:37], 0, s[6:7]
	v_add3_u32 v40, s78, v40, v43
	s_lshl_b32 s8, s41, 5
	v_add_u32_e32 v41, v41, v42
	s_mov_b32 s10, s9
	v_mov_b32_e32 v42, v39
	s_mov_b32 s14, s41
	s_branch .LBB0_173

; #define TID() fresh_tid(wave)
; __device__ __forceinline__ void na_phase(const bf16* qkv, bf16* out, const float* rpb, ldsp lds, int vcu, int G, int tid_in) {
;     ...
;     if (wave >= 4) return;
;     constexpr size_t PITCH = 128, PLANE = pg8::PLANE; constexpr int NUNITS = 2048;
;     const int per = (NUNITS + G - 1) / G; const int u_lo = vcu * per, u_hi = (u_lo + per < NUNITS) ? u_lo + per : NUNITS;
;     for (int U2 = 2 * u_lo; U2 < 2 * u_hi; ++U2) { const int U = U2 >> 1;
; __global__ void __launch_bounds__(NWAVES * 64, 2) mk_fwd(Args args) {
;     ...
;     if (wave >= 4) {
;         const int lane = TID() & 63, gw4 = vcu * 4 + (wave - 4), NGW4 = G * 4;
;         convert_matrix(args.in[4], DM, DM, (bf16*)(ws + WS_WO0), nullptr, 0, 1.f, scr, gw4, NGW4, lane);
;         convert_matrix(args.in[6], DM, DFF, (bf16*)(ws + WS_W10), args.in[5], 0, 1.f, scr, gw4, NGW4, lane);
;         convert_matrix(args.in[7], DFF, DM, (bf16*)(ws + WS_W20), nullptr, 0, 1.f, scr, gw4, NGW4, lane);
;         convert_matrix(args.in[9], DM, NQKV1, (bf16*)(ws + WS_WQKV1), args.in[8], 2, QS, scr, gw4, NGW4, lane);
;     }
.Lhja_reenter:
	s_mov_b32 s99, 1
	s_lshr_b32 s60, s81, 6
	s_sub_i32 s60, s60, 4
	v_add_u32_e32 v0, s81, v252
	s_branch .Lhja_entry
